# speedup vs baseline: 1.0033x; 1.0033x over previous
; DI int my_tid() { int t = threadIdx.x; asm volatile("" : "+v"(t)); return t; }
; DI int my_block() { int b = blockIdx.x; asm volatile("" : "+s"(b)); return b; }
; #define G_STAGE(bufoff, gbase, voff) do { _Pragma("unroll") for (int _i = 0; _i < 2; ++_i) \
;         __builtin_amdgcn_global_load_lds((const unsigned*)((const char*)(gbase) + (voff)[_i]), (LAS unsigned*)(lds + (bufoff) + ldsw + _i * 8192), 16, 0, 0); } while (0)
; #define G_WAIT_V(n) asm volatile("s_waitcnt vmcnt(" #n ")" ::: "memory")
; #define G_BAR __builtin_amdgcn_s_barrier()
;   DI int brow_of(int R) const { return (R & ~31) + perm32(R & 31); }
; template <class J>
; DI void gemm_phase(LAS unsigned char* lds, const J& job) {
;   const int tid = my_tid(), wid = __builtin_amdgcn_readfirstlane(tid >> 6), lane = tid & 63, wr = wid >> 2, wc = wid & 3, fr = lane & 15, fq = lane >> 4;
;   const int nt = job.nt;
;   unsigned voffA[2], voffB[2];
; #pragma unroll
;   for (int i = 0; i < 2; ++i) { int R, C; stage_rc(tid * 16 + i * 8192, R, C); const int Rb = job.brow_of(R);
;     voffA[i] = (unsigned)(R * job.lda + C) * 2u; voffB[i] = (unsigned)(Rb * job.ldb + C) * 2u; }
;   const size_t kstep = (size_t)(BK * 2);
;   const size_t hstepA = (size_t)HALF * job.lda * 2, hstepB = (size_t)job.bhalf_rows() * job.ldb * 2;
;   const unsigned ldsw = (unsigned)wid * 1024u;
;   const int aoff = lds_byte(wr * 64 + fr, fq * 8), boff = lds_byte(wc * 32 + fr, fq * 8);
;     ...
;   Unit cur, nxt; int ui = 0;
;   if (!job.next(0, cur)) return;
;   f32x4 acc[2][2][4][2];
; #pragma unroll
;   for (int a = 0; a < 2; ++a)
; #pragma unroll
;     for (int b = 0; b < 2; ++b)
; #pragma unroll
;       for (int m = 0; m < 4; ++m)
; #pragma unroll
;         for (int n = 0; n < 2; ++n) acc[a][b][m][n] = (f32x4){0.f, 0.f, 0.f, 0.f};
;   bf16x8 At[4][2], B0[2][2], B1[2][2];
;   const char* cA = job.aptr(cur); const char* cB = job.bptr(cur);
;   const int koff = (my_block() & 7) * (nt >> 3), kmask = nt - 1;
;     ...
;   G_STAGE(G_SB(0, 0), cB + G_KT(0), voffB); G_STAGE(G_SA(0, 0), cA + G_KT(0), voffA); G_STAGE(G_SB(0, 1), cB + hstepB + G_KT(0), voffB); G_STAGE(G_SA(0, 1), cA + hstepA + G_KT(0), voffA);
;   if (wr == 1) G_BAR;
;   G_WAIT_V(4); G_BAR;
;   G_STAGE(G_SB(1, 0), cB + G_KT(1), voffB); G_STAGE(G_SA(1, 0), cA + G_KT(1), voffA); G_STAGE(G_SB(1, 1), cB + hstepB + G_KT(1), voffB);
;   G_WAIT_V(6); G_BAR;
.LBB0_274:
	v_readlane_b32 s0, v255, 14
	s_load_dwordx2 s[10:11], s[60:61], 0xc8
	v_readlane_b32 s1, v255, 15
	s_and_b64 s[6:7], s[0:1], exec
	s_cselect_b32 s0, 0x3800000, 0
	s_add_u32 s12, s50, s0
	s_addc_u32 s13, s51, 0
	s_andn2_b64 vcc, exec, s[16:17]
	s_cbranch_vccnz .LBB0_318
	v_bfe_i32 v3, v0, 27, 1
	v_lshlrev_b32_e32 v1, 4, v0
	v_lshrrev_b32_e32 v3, 22, v3
	v_add_u32_e32 v3, v1, v3
	v_and_b32_e32 v3, 0xfffffc00, v3
	v_ashrrev_i32_e32 v2, 31, v0
	v_sub_u32_e32 v3, v1, v3
	v_lshrrev_b32_e32 v2, 26, v2
	s_waitcnt vmcnt(0)
	v_lshrrev_b32_e32 v4, 4, v3
	v_add_u32_e32 v2, v0, v2
	v_bitop3_b32 v4, v4, v3, 32 bitop3:0x6c
	v_ashrrev_i32_e32 v3, 31, v3
	v_ashrrev_i32_e32 v2, 6, v2
	v_lshrrev_b32_e32 v3, 26, v3
	v_lshlrev_b32_e32 v5, 3, v2
	v_add_u32_e32 v3, v4, v3
	v_and_b32_e32 v5, -16, v5
	v_ashrrev_i32_e32 v3, 6, v3
	v_add_u32_e32 v5, v3, v5
	v_mul_i32_i24_e32 v3, 64, v3
	v_sub_u32_e32 v3, v4, v3
	v_lshlrev_b32_e32 v2, 5, v2
	v_ashrrev_i16_sdwa v3, v220, sext(v3) dst_sel:DWORD dst_unused:UNUSED_PAD src0_sel:DWORD src1_sel:BYTE_0
	v_lshlrev_b32_e32 v4, 1, v5
	v_lshrrev_b32_e32 v6, 2, v5
	v_and_b32_e32 v2, 32, v2
	v_bfe_i32 v3, v3, 0, 16
	v_and_b32_e32 v4, 24, v4
	v_and_b32_e32 v6, 4, v6
	v_and_b32_e32 v7, 0xfffe3, v5
	v_or3_b32 v4, v7, v6, v4
	v_add_lshl_u32 v2, v2, v3, 1
	v_add_u32_e32 v1, 0x2000, v1
	v_ashrrev_i32_e32 v2, 31, v1
	v_lshrrev_b32_e32 v2, 22, v2
	v_add_u32_e32 v2, v1, v2
	s_ashr_i32 s16, s4, 6
	s_ashr_i32 s9, s8, 31
	s_ashr_i32 s65, s64, 31
	s_ashr_i32 s6, s4, 8
	v_ashrrev_i32_e32 v2, 10, v2
	s_lshl_b32 s5, s16, 10
	s_lshl_b64 s[18:19], s[8:9], 20
	s_lshl_b64 s[14:15], s[64:65], 20
	v_mul_i32_i24_e32 v3, 0x400, v2
	s_add_u32 s66, s12, s14
	s_mov_b32 s7, s2
	v_sub_u32_e32 v1, v1, v3
	s_addc_u32 s67, s13, s15
	s_lshl_b32 s0, s7, 2
	v_lshrrev_b32_e32 v3, 4, v1
	s_and_b32 s0, s0, 28
	v_bitop3_b32 v1, v3, v1, 32 bitop3:0x6c
	s_lshl_b32 s14, s0, 7
	v_ashrrev_i32_e32 v4, 31, v1
	s_add_u32 s20, s66, s14
	v_lshrrev_b32_e32 v4, 26, v4
	s_addc_u32 s21, s67, 0
	s_add_i32 s15, s5, 0x100
	v_lshlrev_b32_e32 v3, 3, v2
	v_add_u32_e32 v4, v1, v4
	v_and_b32_e32 v8, 63, v144
	v_lshrrev_b32_e32 v9, 6, v144
	v_lshrrev_b32_e32 v10, 3, v8
	v_lshrrev_b32_e32 v11, 4, v8
	v_and_b32_e32 v12, 1, v9
	v_lshl_or_b32 v11, v12, 2, v11
	v_and_b32_e32 v13, 7, v8
	v_xor_b32_e32 v13, v13, v11
	v_lshlrev_b32_e32 v13, 4, v13
	v_lshl_add_u32 v14, v9, 3, v10
	v_lshl_add_u32 v128, v14, 12, v13
	v_add_u32_e32 v130, 0x40000, v128
	v_lshrrev_b32_e32 v14, 2, v9
	v_lshlrev_b32_e32 v14, 5, v14
	v_lshl_or_b32 v14, v12, 4, v14
	v_lshrrev_b32_e32 v15, 2, v10
	v_lshl_or_b32 v14, v15, 3, v14
	v_bfe_u32 v15, v9, 1, 1
	v_lshl_or_b32 v14, v15, 2, v14
	v_and_b32_e32 v15, 3, v10
	v_or_b32_e32 v14, v14, v15
	v_lshl_add_u32 v146, v14, 12, v13
	v_add_u32_e32 v132, 0x40000, v146
	s_add_i32 m0, s15, 0x10000
	v_and_b32_e32 v3, -16, v3
	v_ashrrev_i32_e32 v5, 6, v4
	v_and_b32_e32 v4, 0xc0, v4
	global_load_lds_dwordx4 v146, s[20:21]
	s_add_i32 m0, s15, 0x12000
	v_add_u32_e32 v3, v5, v3
	v_sub_u32_e32 v1, v1, v4
	s_add_u32 s68, s58, s18
	v_lshlrev_b32_e32 v2, 5, v2
	v_ashrrev_i16_sdwa v1, v220, sext(v1) dst_sel:DWORD dst_unused:UNUSED_PAD src0_sel:DWORD src1_sel:BYTE_0
	v_lshlrev_b32_e32 v4, 1, v3
	v_lshrrev_b32_e32 v5, 2, v3
	s_addc_u32 s69, s59, s19
	v_and_b32_e32 v2, 32, v2
	v_bfe_i32 v1, v1, 0, 16
	v_and_b32_e32 v4, 24, v4
	v_and_b32_e32 v5, 4, v5
	v_and_b32_e32 v6, 0xfffe3, v3
	s_add_u32 s18, s68, s14
	v_or3_b32 v4, v6, v5, v4
	v_add_lshl_u32 v1, v2, v1, 1
	s_addc_u32 s19, s69, 0
	s_add_i32 s24, s15, 0x2000
	s_add_u32 s9, s66, 0x80000
	global_load_lds_dwordx4 v132, s[20:21]
	s_mov_b32 m0, s15
	s_addc_u32 s17, s67, 0
	global_load_lds_dwordx4 v128, s[18:19]
	s_mov_b32 m0, s24
	s_add_u32 s20, s9, s14
	global_load_lds_dwordx4 v130, s[18:19]
	s_addc_u32 s21, s17, 0
	s_add_i32 m0, s15, 0x14000
	v_writelane_b32 v255, s36, 20
	global_load_lds_dwordx4 v146, s[20:21]
	s_add_i32 m0, s15, 0x16000
	s_add_u32 s18, s18, 0x80000
	s_addc_u32 s19, s19, 0
	s_add_i32 s25, s15, 0x4000
	v_writelane_b32 v255, s37, 21
	global_load_lds_dwordx4 v132, s[20:21]
	s_mov_b32 m0, s25
	s_add_i32 s36, s15, 0x6000
	global_load_lds_dwordx4 v128, s[18:19]
	s_mov_b32 m0, s36
	s_cmp_lg_u32 s6, 1
	global_load_lds_dwordx4 v130, s[18:19]
	s_cbranch_scc1 .LBB0_277
	s_barrier
.LBB0_277:
	s_lshl_b32 s1, s16, 5
	s_and_b32 s38, s1, 0x60
	s_lshl_b32 s37, s6, 6
	s_lshl_b32 s0, s6, 13
	s_lshl_b32 s1, s38, 7
	s_or_b32 s44, s14, 0x80
	s_add_u32 s18, s66, s44
	s_addc_u32 s19, s67, 0
	s_add_i32 m0, s15, 0x18000
	v_lshl_add_u64 v[2:3], s[18:19], 0, v[146:147]
	v_mov_b32_e32 v133, v147
	s_waitcnt vmcnt(4)
	s_barrier
	global_load_lds_dwordx4 v[2:3], off
	s_add_i32 m0, s15, 0x1a000
	v_lshl_add_u64 v[2:3], s[18:19], 0, v[132:133]
	s_add_u32 s18, s68, s44
	v_mov_b32_e32 v129, v147
	s_addc_u32 s19, s69, 0
	s_add_i32 s45, s15, 0x8000
	s_add_i32 s65, s15, 0xa000
	v_mov_b32_e32 v131, v147
	global_load_lds_dwordx4 v[2:3], off
	v_lshl_add_u64 v[2:3], s[18:19], 0, v[128:129]
	s_mov_b32 m0, s45
	s_add_u32 s16, s9, s44
	global_load_lds_dwordx4 v[2:3], off
	v_lshl_add_u64 v[2:3], s[18:19], 0, v[130:131]
	s_mov_b32 m0, s65
	s_addc_u32 s17, s17, 0
	global_load_lds_dwordx4 v[2:3], off
	s_add_i32 m0, s15, 0x1c000
	v_lshl_add_u64 v[2:3], s[16:17], 0, v[146:147]
	global_load_lds_dwordx4 v[2:3], off
	v_lshl_add_u64 v[2:3], s[16:17], 0, v[132:133]
	s_add_i32 m0, s15, 0x1e000
	v_bfe_u32 v149, v0, 4, 2
	global_load_lds_dwordx4 v[2:3], off
	v_and_b32_e32 v148, 15, v0
	v_lshrrev_b32_e32 v1, 1, v148
	v_xor_b32_e32 v1, v1, v149
	v_lshlrev_b32_e32 v1, 4, v1
	v_lshl_or_b32 v1, v148, 7, v1
	v_mov_b32_e32 v0, 0
	v_bitop3_b32 v2, v1, s0, v0 bitop3:0xde
	v_bitop3_b32 v150, v1, s1, v0 bitop3:0xde
	v_readlane_b32 s0, v255, 14
	s_and_b32 s78, s43, 7
	v_readlane_b32 s1, v255, 15
	s_and_b64 s[16:17], s[0:1], exec
	s_cselect_b32 s0, 0x2000000, 0
	s_waitcnt lgkmcnt(0)
	s_add_u32 s83, s10, s0
	s_addc_u32 s86, s11, 0
	s_lshl_b32 s0, s7, 9
	s_waitcnt vmcnt(6)
	s_or_b32 s87, s0, 0x180
	s_and_b32 s0, s7, 7
	s_lshl_b32 s94, s0, 9
	s_mov_b32 s79, 0
	s_bitset1_b32 s94, 7
	v_add_u32_e32 v151, 0x100, v2
	v_xor_b32_e32 v208, 64, v151
	v_xor_b32_e32 v209, 64, v150
	s_movk_i32 s2, 0xc1
	s_barrier
	s_branch .LBB0_279

; #define G_STAGE(bufoff, gbase, voff) do { _Pragma("unroll") for (int _i = 0; _i < 2; ++_i) \
;         __builtin_amdgcn_global_load_lds((const unsigned*)((const char*)(gbase) + (voff)[_i]), (LAS unsigned*)(lds + (bufoff) + ldsw + _i * 8192), 16, 0, 0); } while (0)
; #define G_LDA(dst, b, h) do { _Pragma("unroll") for (int m = 0; m < 4; ++m) _Pragma("unroll") for (int k = 0; k < 2; ++k) dst[m][k] = *(const LAS bf16x8*)(lds + G_SA(b, h) + aoff + m * 2048 + k * 1024); } while (0)
; #define G_LDB(dst, b, h) do { _Pragma("unroll") for (int n = 0; n < 2; ++n) _Pragma("unroll") for (int k = 0; k < 2; ++k) dst[n][k] = *(const LAS bf16x8*)(lds + G_SB(b, h) + boff + n * 2048 + k * 1024); } while (0)
; #define G_MMA(ai, bj, At, Bt) do { __builtin_amdgcn_s_setprio(1); _Pragma("unroll") for (int m = 0; m < 4; ++m) _Pragma("unroll") for (int n = 0; n < 2; ++n) _Pragma("unroll") for (int k = 0; k < 2; ++k) \
;         acc[ai][bj][m][n] = __builtin_amdgcn_mfma_f32_16x16x32_bf16(Bt[n][k], At[m][k], acc[ai][bj][m][n], 0, 0, 0); __builtin_amdgcn_s_setprio(0); } while (0)
; #define G_WAIT_L(n) asm volatile("s_waitcnt lgkmcnt(" #n ")" ::: "memory")
; #define G_BAR __builtin_amdgcn_s_barrier()
; #define G_SCHED __builtin_amdgcn_sched_barrier(0)
; template <class J>
; DI void gemm_phase(LAS unsigned char* lds, const J& job) {
;     ...
;       const bool last = (t == nt - 2);
;       const char* a1 = cA + G_KT(t + 1);
;       const char* a2 = last ? nA + G_KT(0) : cA + G_KT(t + 2); const char* b2 = last ? nB + G_KT(0) : cB + G_KT(t + 2);
;       const char* a3 = last ? nA + G_KT(1) : cA + G_KT(t + 3); const char* b3 = last ? nB + G_KT(1) : cB + G_KT(t + 3);
;       G_LDB(B0, 0, 0); G_SCHED; G_LDA(At, 0, 0); G_STAGE(G_SA(1, 1), a1 + hstepA, voffA);
;       G_WAIT_L(8); G_BAR; G_WAIT_L(0); G_MMA(0, 0, At, B0); G_BAR; G_SCHED;
;       G_LDB(B1, 0, 1); G_STAGE(G_SB(0, 0), b2, voffB);
;       G_BAR; G_WAIT_L(0); G_MMA(0, 1, At, B1); G_BAR;
;       G_LDA(At, 0, 1); G_STAGE(G_SA(0, 0), a2, voffA);
;       G_BAR; G_WAIT_L(0); G_MMA(1, 0, At, B0); G_BAR; G_SCHED;
.LBB0_282:
	s_add_i32 s1, s56, 0xffffff80
	s_and_b32 s0, s7, 0xf80
	s_and_b32 s1, s1, 0xf00
	s_add_u32 s10, s68, s1
	s_addc_u32 s11, s69, 0
	s_add_u32 s1, s66, s1
	s_addc_u32 s57, s67, 0
	s_and_b32 s70, s56, 0xf80
	s_add_u32 s71, s68, s70
	s_addc_u32 s72, s69, 0
	s_add_u32 s70, s66, s70
	s_addc_u32 s80, s67, 0
	s_cmp_eq_u32 s6, 28
	s_cselect_b32 s75, s46, s11
	s_cselect_b32 s74, s21, s10
	s_cselect_b32 s77, s96, s57
	s_cselect_b32 s76, s47, s1
	s_cselect_b32 s73, s97, s72
	s_cselect_b32 s72, s33, s71
	s_cselect_b32 s71, vcc_hi, s80
	s_cselect_b32 s70, vcc_lo, s70
	s_add_i32 s1, s84, 0x100
	v_add_u32_e32 v152, s1, v150
	v_add_u32_e32 v156, s1, v209
	ds_read_b128 v[134:137], v152
	ds_read_b128 v[138:141], v156
	ds_read_b128 v[152:155], v152 offset:2048
	ds_read_b128 v[156:159], v156 offset:2048
	s_add_u32 s10, s9, s0
	s_addc_u32 s11, s19, 0
	v_lshl_add_u64 v[142:143], s[10:11], 0, v[128:129]
	s_add_i32 m0, s15, 0xc000
	ds_read_b128 v[160:163], v151
	ds_read_b128 v[164:167], v208
	ds_read_b128 v[168:171], v151 offset:2048
	ds_read_b128 v[172:175], v208 offset:2048
	ds_read_b128 v[176:179], v151 offset:4096
	ds_read_b128 v[180:183], v208 offset:4096
	ds_read_b128 v[184:187], v151 offset:6144
	ds_read_b128 v[188:191], v208 offset:6144
	global_load_lds_dwordx4 v[142:143], off
	v_lshl_add_u64 v[142:143], s[10:11], 0, v[130:131]
	s_add_i32 m0, s15, 0xe000
	s_nop 0
	global_load_lds_dwordx4 v[142:143], off
	s_waitcnt lgkmcnt(8)
	s_barrier
	s_waitcnt lgkmcnt(0)
	s_setprio 1
	s_waitcnt lgkmcnt(0)
	v_mfma_f32_16x16x32_bf16 v[124:127], v[134:137], v[160:163], v[124:127]
	v_mfma_f32_16x16x32_bf16 v[120:123], v[152:155], v[160:163], v[120:123]
	v_mfma_f32_16x16x32_bf16 v[108:111], v[134:137], v[168:171], v[108:111]
	v_mfma_f32_16x16x32_bf16 v[104:107], v[152:155], v[168:171], v[104:107]
	v_mfma_f32_16x16x32_bf16 v[92:95], v[134:137], v[176:179], v[92:95]
	v_mfma_f32_16x16x32_bf16 v[88:91], v[152:155], v[176:179], v[88:91]
	v_mfma_f32_16x16x32_bf16 v[76:79], v[134:137], v[184:187], v[76:79]
	v_mfma_f32_16x16x32_bf16 v[72:75], v[152:155], v[184:187], v[72:75]
	v_mfma_f32_16x16x32_bf16 v[124:127], v[138:141], v[164:167], v[124:127]
	v_mfma_f32_16x16x32_bf16 v[120:123], v[156:159], v[164:167], v[120:123]
	v_mfma_f32_16x16x32_bf16 v[108:111], v[138:141], v[172:175], v[108:111]
	v_mfma_f32_16x16x32_bf16 v[104:107], v[156:159], v[172:175], v[104:107]
	v_mfma_f32_16x16x32_bf16 v[92:95], v[138:141], v[180:183], v[92:95]
	v_mfma_f32_16x16x32_bf16 v[88:91], v[156:159], v[180:183], v[88:91]
	v_mfma_f32_16x16x32_bf16 v[76:79], v[138:141], v[188:191], v[76:79]
	v_mfma_f32_16x16x32_bf16 v[72:75], v[156:159], v[188:191], v[72:75]
	s_setprio 0
	s_barrier
	s_add_i32 s0, s85, 0x100
	v_add_u32_e32 v200, s0, v150
	v_add_u32_e32 v204, s0, v209
	s_add_i32 s1, s1, s5
	ds_read_b128 v[192:195], v200
	ds_read_b128 v[196:199], v204
	ds_read_b128 v[200:203], v200 offset:2048
	ds_read_b128 v[204:207], v204 offset:2048
	v_lshl_add_u64 v[142:143], s[76:77], 0, v[146:147]
	s_mov_b32 m0, s1
	s_nop 0
	global_load_lds_dwordx4 v[142:143], off
	v_lshl_add_u64 v[142:143], s[76:77], 0, v[132:133]
	s_add_i32 m0, s1, 0x2000
	s_nop 0
	global_load_lds_dwordx4 v[142:143], off
	s_barrier
	s_waitcnt lgkmcnt(0)
	s_setprio 1
	s_waitcnt lgkmcnt(0)
	v_mfma_f32_16x16x32_bf16 v[116:119], v[192:195], v[160:163], v[116:119]
	v_mfma_f32_16x16x32_bf16 v[112:115], v[200:203], v[160:163], v[112:115]
	v_mfma_f32_16x16x32_bf16 v[100:103], v[192:195], v[168:171], v[100:103]
	v_mfma_f32_16x16x32_bf16 v[96:99], v[200:203], v[168:171], v[96:99]
	v_mfma_f32_16x16x32_bf16 v[84:87], v[192:195], v[176:179], v[84:87]
	v_mfma_f32_16x16x32_bf16 v[80:83], v[200:203], v[176:179], v[80:83]
	v_mfma_f32_16x16x32_bf16 v[68:71], v[192:195], v[184:187], v[68:71]
	v_mfma_f32_16x16x32_bf16 v[64:67], v[200:203], v[184:187], v[64:67]
	v_mfma_f32_16x16x32_bf16 v[116:119], v[196:199], v[164:167], v[116:119]
	v_mfma_f32_16x16x32_bf16 v[112:115], v[204:207], v[164:167], v[112:115]
	v_mfma_f32_16x16x32_bf16 v[100:103], v[196:199], v[172:175], v[100:103]
	v_mfma_f32_16x16x32_bf16 v[96:99], v[204:207], v[172:175], v[96:99]
	v_mfma_f32_16x16x32_bf16 v[84:87], v[196:199], v[180:183], v[84:87]
	v_mfma_f32_16x16x32_bf16 v[80:83], v[204:207], v[180:183], v[80:83]
	v_mfma_f32_16x16x32_bf16 v[68:71], v[196:199], v[188:191], v[68:71]
	v_mfma_f32_16x16x32_bf16 v[64:67], v[204:207], v[188:191], v[64:67]
	s_setprio 0
	s_mov_b32 m0, s15
	v_lshl_add_u64 v[142:143], s[74:75], 0, v[128:129]
	s_barrier
	ds_read_b128 v[160:163], v151 offset:16384
	ds_read_b128 v[164:167], v208 offset:16384
	ds_read_b128 v[168:171], v151 offset:18432
	ds_read_b128 v[172:175], v208 offset:18432
	ds_read_b128 v[176:179], v151 offset:20480
	ds_read_b128 v[180:183], v208 offset:20480
	ds_read_b128 v[184:187], v151 offset:22528
	ds_read_b128 v[188:191], v208 offset:22528
	global_load_lds_dwordx4 v[142:143], off
	v_lshl_add_u64 v[142:143], s[74:75], 0, v[130:131]
	s_mov_b32 m0, s24
	s_nop 0
	global_load_lds_dwordx4 v[142:143], off
	s_barrier
	s_waitcnt lgkmcnt(0)
	s_setprio 1
	s_waitcnt lgkmcnt(0)
	v_mfma_f32_16x16x32_bf16 v[60:63], v[134:137], v[160:163], v[60:63]
	v_mfma_f32_16x16x32_bf16 v[56:59], v[152:155], v[160:163], v[56:59]
	v_mfma_f32_16x16x32_bf16 v[44:47], v[134:137], v[168:171], v[44:47]
	v_mfma_f32_16x16x32_bf16 v[40:43], v[152:155], v[168:171], v[40:43]
	v_mfma_f32_16x16x32_bf16 v[28:31], v[134:137], v[176:179], v[28:31]
	v_mfma_f32_16x16x32_bf16 v[24:27], v[152:155], v[176:179], v[24:27]
	v_mfma_f32_16x16x32_bf16 v[12:15], v[134:137], v[184:187], v[12:15]
	v_mfma_f32_16x16x32_bf16 v[8:11], v[152:155], v[184:187], v[8:11]
	v_mfma_f32_16x16x32_bf16 v[60:63], v[138:141], v[164:167], v[60:63]
	v_mfma_f32_16x16x32_bf16 v[56:59], v[156:159], v[164:167], v[56:59]
	v_mfma_f32_16x16x32_bf16 v[44:47], v[138:141], v[172:175], v[44:47]
	v_mfma_f32_16x16x32_bf16 v[40:43], v[156:159], v[172:175], v[40:43]
	v_mfma_f32_16x16x32_bf16 v[28:31], v[138:141], v[180:183], v[28:31]
	v_mfma_f32_16x16x32_bf16 v[24:27], v[156:159], v[180:183], v[24:27]
	v_mfma_f32_16x16x32_bf16 v[12:15], v[138:141], v[188:191], v[12:15]
	v_mfma_f32_16x16x32_bf16 v[8:11], v[156:159], v[188:191], v[8:11]
	s_setprio 0
	s_barrier
; #define G_STAGE(bufoff, gbase, voff) do { _Pragma("unroll") for (int _i = 0; _i < 2; ++_i) \
;         __builtin_amdgcn_global_load_lds((const unsigned*)((const char*)(gbase) + (voff)[_i]), (LAS unsigned*)(lds + (bufoff) + ldsw + _i * 8192), 16, 0, 0); } while (0)
; #define G_LDA(dst, b, h) do { _Pragma("unroll") for (int m = 0; m < 4; ++m) _Pragma("unroll") for (int k = 0; k < 2; ++k) dst[m][k] = *(const LAS bf16x8*)(lds + G_SA(b, h) + aoff + m * 2048 + k * 1024); } while (0)
; #define G_LDB(dst, b, h) do { _Pragma("unroll") for (int n = 0; n < 2; ++n) _Pragma("unroll") for (int k = 0; k < 2; ++k) dst[n][k] = *(const LAS bf16x8*)(lds + G_SB(b, h) + boff + n * 2048 + k * 1024); } while (0)
; #define G_MMA(ai, bj, At, Bt) do { __builtin_amdgcn_s_setprio(1); _Pragma("unroll") for (int m = 0; m < 4; ++m) _Pragma("unroll") for (int n = 0; n < 2; ++n) _Pragma("unroll") for (int k = 0; k < 2; ++k) \
;         acc[ai][bj][m][n] = __builtin_amdgcn_mfma_f32_16x16x32_bf16(Bt[n][k], At[m][k], acc[ai][bj][m][n], 0, 0, 0); __builtin_amdgcn_s_setprio(0); } while (0)
; #define G_WAIT_V(n) asm volatile("s_waitcnt vmcnt(" #n ")" ::: "memory")
; #define G_WAIT_L(n) asm volatile("s_waitcnt lgkmcnt(" #n ")" ::: "memory")
; #define G_BAR __builtin_amdgcn_s_barrier()
; #define G_SCHED __builtin_amdgcn_sched_barrier(0)
; template <class J>
; DI void gemm_phase(LAS unsigned char* lds, const J& job) {
;     ...
;       G_STAGE(G_SB(0, 1), b2 + hstepB, voffB);
;       G_WAIT_V(6); G_BAR; G_MMA(1, 1, At, B1); G_BAR;
;       G_LDB(B0, 1, 0); G_SCHED; G_LDA(At, 1, 0); G_STAGE(G_SA(0, 1), a2 + hstepA, voffA);
;       G_WAIT_L(8); G_BAR; G_WAIT_L(0); G_MMA(0, 0, At, B0); G_BAR; G_SCHED;
;       G_LDB(B1, 1, 1); G_STAGE(G_SB(1, 0), b3, voffB);
;       G_BAR; G_WAIT_L(0); G_MMA(0, 1, At, B1); G_BAR;
;       G_LDA(At, 1, 1); G_STAGE(G_SA(1, 0), a3, voffA);
	s_add_u32 s10, s76, 0x80000
	s_addc_u32 s11, s77, 0
	s_add_i32 s0, s0, s5
	v_lshl_add_u64 v[134:135], s[10:11], 0, v[146:147]
	s_mov_b32 m0, s0
	s_nop 0
	global_load_lds_dwordx4 v[134:135], off
	v_lshl_add_u64 v[134:135], s[10:11], 0, v[132:133]
	s_add_i32 m0, s0, 0x2000
	s_nop 0
	global_load_lds_dwordx4 v[134:135], off
	s_waitcnt vmcnt(6)
	s_barrier
	s_setprio 1
	v_mfma_f32_16x16x32_bf16 v[52:55], v[192:195], v[160:163], v[52:55]
	v_mfma_f32_16x16x32_bf16 v[48:51], v[200:203], v[160:163], v[48:51]
	v_mfma_f32_16x16x32_bf16 v[36:39], v[192:195], v[168:171], v[36:39]
	v_mfma_f32_16x16x32_bf16 v[32:35], v[200:203], v[168:171], v[32:35]
	v_mfma_f32_16x16x32_bf16 v[20:23], v[192:195], v[176:179], v[20:23]
	v_mfma_f32_16x16x32_bf16 v[16:19], v[200:203], v[176:179], v[16:19]
	v_mfma_f32_16x16x32_bf16 v[4:7], v[192:195], v[184:187], v[4:7]
	v_mfma_f32_16x16x32_bf16 v[0:3], v[200:203], v[184:187], v[0:3]
	v_mfma_f32_16x16x32_bf16 v[52:55], v[196:199], v[164:167], v[52:55]
	v_mfma_f32_16x16x32_bf16 v[48:51], v[204:207], v[164:167], v[48:51]
	v_mfma_f32_16x16x32_bf16 v[36:39], v[196:199], v[172:175], v[36:39]
	v_mfma_f32_16x16x32_bf16 v[32:35], v[204:207], v[172:175], v[32:35]
	v_mfma_f32_16x16x32_bf16 v[20:23], v[196:199], v[180:183], v[20:23]
	v_mfma_f32_16x16x32_bf16 v[16:19], v[204:207], v[180:183], v[16:19]
	v_mfma_f32_16x16x32_bf16 v[4:7], v[196:199], v[188:191], v[4:7]
	v_mfma_f32_16x16x32_bf16 v[0:3], v[204:207], v[188:191], v[0:3]
	s_setprio 0
	s_add_i32 s0, s88, 0x100
	v_add_u32_e32 v152, s0, v150
	v_add_u32_e32 v156, s0, v209
	s_barrier
	ds_read_b128 v[134:137], v152
	ds_read_b128 v[138:141], v156
	ds_read_b128 v[152:155], v152 offset:2048
	ds_read_b128 v[156:159], v156 offset:2048
	s_add_u32 s10, s74, 0x80000
	s_addc_u32 s11, s75, 0
	s_mov_b32 m0, s25
	v_lshl_add_u64 v[142:143], s[10:11], 0, v[128:129]
	ds_read_b128 v[160:163], v151 offset:32768
	ds_read_b128 v[164:167], v208 offset:32768
	ds_read_b128 v[168:171], v151 offset:34816
	ds_read_b128 v[172:175], v208 offset:34816
	ds_read_b128 v[176:179], v151 offset:36864
	ds_read_b128 v[180:183], v208 offset:36864
	ds_read_b128 v[184:187], v151 offset:38912
	ds_read_b128 v[188:191], v208 offset:38912
	global_load_lds_dwordx4 v[142:143], off
	v_lshl_add_u64 v[142:143], s[10:11], 0, v[130:131]
	s_mov_b32 m0, s36
	s_nop 0
	global_load_lds_dwordx4 v[142:143], off
	s_waitcnt lgkmcnt(8)
	s_barrier
	s_waitcnt lgkmcnt(0)
	s_setprio 1
	s_waitcnt lgkmcnt(0)
	v_mfma_f32_16x16x32_bf16 v[124:127], v[134:137], v[160:163], v[124:127]
	v_mfma_f32_16x16x32_bf16 v[120:123], v[152:155], v[160:163], v[120:123]
	v_mfma_f32_16x16x32_bf16 v[108:111], v[134:137], v[168:171], v[108:111]
	v_mfma_f32_16x16x32_bf16 v[104:107], v[152:155], v[168:171], v[104:107]
	v_mfma_f32_16x16x32_bf16 v[92:95], v[134:137], v[176:179], v[92:95]
	v_mfma_f32_16x16x32_bf16 v[88:91], v[152:155], v[176:179], v[88:91]
	v_mfma_f32_16x16x32_bf16 v[76:79], v[134:137], v[184:187], v[76:79]
	v_mfma_f32_16x16x32_bf16 v[72:75], v[152:155], v[184:187], v[72:75]
	v_mfma_f32_16x16x32_bf16 v[124:127], v[138:141], v[164:167], v[124:127]
	v_mfma_f32_16x16x32_bf16 v[120:123], v[156:159], v[164:167], v[120:123]
	v_mfma_f32_16x16x32_bf16 v[108:111], v[138:141], v[172:175], v[108:111]
	v_mfma_f32_16x16x32_bf16 v[104:107], v[156:159], v[172:175], v[104:107]
	v_mfma_f32_16x16x32_bf16 v[92:95], v[138:141], v[180:183], v[92:95]
	v_mfma_f32_16x16x32_bf16 v[88:91], v[156:159], v[180:183], v[88:91]
	v_mfma_f32_16x16x32_bf16 v[76:79], v[138:141], v[188:191], v[76:79]
	v_mfma_f32_16x16x32_bf16 v[72:75], v[156:159], v[188:191], v[72:75]
	s_setprio 0
	s_barrier
	s_add_i32 s1, s89, 0x100
	v_add_u32_e32 v200, s1, v150
	v_add_u32_e32 v204, s1, v209
	s_add_i32 s0, s0, s5
	ds_read_b128 v[192:195], v200
	ds_read_b128 v[196:199], v204
	ds_read_b128 v[200:203], v200 offset:2048
	ds_read_b128 v[204:207], v204 offset:2048
	v_lshl_add_u64 v[142:143], s[70:71], 0, v[146:147]
	s_mov_b32 m0, s0
	s_nop 0
	global_load_lds_dwordx4 v[142:143], off
	v_lshl_add_u64 v[142:143], s[70:71], 0, v[132:133]
	s_add_i32 m0, s0, 0x2000
	s_nop 0
	global_load_lds_dwordx4 v[142:143], off
	s_barrier
	s_waitcnt lgkmcnt(0)
	s_setprio 1
	s_waitcnt lgkmcnt(0)
	v_mfma_f32_16x16x32_bf16 v[116:119], v[192:195], v[160:163], v[116:119]
	v_mfma_f32_16x16x32_bf16 v[112:115], v[200:203], v[160:163], v[112:115]
	v_mfma_f32_16x16x32_bf16 v[100:103], v[192:195], v[168:171], v[100:103]
	v_mfma_f32_16x16x32_bf16 v[96:99], v[200:203], v[168:171], v[96:99]
	v_mfma_f32_16x16x32_bf16 v[84:87], v[192:195], v[176:179], v[84:87]
	v_mfma_f32_16x16x32_bf16 v[80:83], v[200:203], v[176:179], v[80:83]
	v_mfma_f32_16x16x32_bf16 v[68:71], v[192:195], v[184:187], v[68:71]
	v_mfma_f32_16x16x32_bf16 v[64:67], v[200:203], v[184:187], v[64:67]
	v_mfma_f32_16x16x32_bf16 v[116:119], v[196:199], v[164:167], v[116:119]
	v_mfma_f32_16x16x32_bf16 v[112:115], v[204:207], v[164:167], v[112:115]
	v_mfma_f32_16x16x32_bf16 v[100:103], v[196:199], v[172:175], v[100:103]
	v_mfma_f32_16x16x32_bf16 v[96:99], v[204:207], v[172:175], v[96:99]
	v_mfma_f32_16x16x32_bf16 v[84:87], v[196:199], v[180:183], v[84:87]
	v_mfma_f32_16x16x32_bf16 v[80:83], v[204:207], v[180:183], v[80:83]
	v_mfma_f32_16x16x32_bf16 v[68:71], v[196:199], v[188:191], v[68:71]
	v_mfma_f32_16x16x32_bf16 v[64:67], v[204:207], v[188:191], v[64:67]
	s_setprio 0
	s_mov_b32 m0, s45
	v_lshl_add_u64 v[142:143], s[72:73], 0, v[128:129]
	s_barrier
; DI unsigned pk2(float lo, float hi) { unsigned r; asm("v_cvt_pk_bf16_f32 %0, %1, %2" : "=v"(r) : "v"(lo), "v"(hi)); return r; }
; #define G_STAGE(bufoff, gbase, voff) do { _Pragma("unroll") for (int _i = 0; _i < 2; ++_i) \
;         __builtin_amdgcn_global_load_lds((const unsigned*)((const char*)(gbase) + (voff)[_i]), (LAS unsigned*)(lds + (bufoff) + ldsw + _i * 8192), 16, 0, 0); } while (0)
; #define G_LDA(dst, b, h) do { _Pragma("unroll") for (int m = 0; m < 4; ++m) _Pragma("unroll") for (int k = 0; k < 2; ++k) dst[m][k] = *(const LAS bf16x8*)(lds + G_SA(b, h) + aoff + m * 2048 + k * 1024); } while (0)
; #define G_MMA(ai, bj, At, Bt) do { __builtin_amdgcn_s_setprio(1); _Pragma("unroll") for (int m = 0; m < 4; ++m) _Pragma("unroll") for (int n = 0; n < 2; ++n) _Pragma("unroll") for (int k = 0; k < 2; ++k) \
;         acc[ai][bj][m][n] = __builtin_amdgcn_mfma_f32_16x16x32_bf16(Bt[n][k], At[m][k], acc[ai][bj][m][n], 0, 0, 0); __builtin_amdgcn_s_setprio(0); } while (0)
; #define G_WAIT_V(n) asm volatile("s_waitcnt vmcnt(" #n ")" ::: "memory")
; #define G_WAIT_L(n) asm volatile("s_waitcnt lgkmcnt(" #n ")" ::: "memory")
; #define G_BAR __builtin_amdgcn_s_barrier()
; #define G_SCHED __builtin_amdgcn_sched_barrier(0)
; template <class J>
; DI void gemm_phase(LAS unsigned char* lds, const J& job) {
;     ...
;       G_LDA(At, 1, 1); G_STAGE(G_SA(1, 0), a3, voffA);
;       G_BAR; G_WAIT_L(0); G_MMA(1, 0, At, B0); G_BAR; G_SCHED;
;       G_STAGE(G_SB(1, 1), b3 + hstepB, voffB);
;       G_WAIT_V(6); G_BAR; G_MMA(1, 1, At, B1); G_BAR;
;   DI void epi(const Acc& acc, const Unit& u, int wr, int wc, int fr, int fq) const {
;     ...
;         const int rl = ai * HALF + wr * 64 + m * 16 + fr;
; #pragma unroll
;         for (int bj = 0; bj < 2; ++bj) {
;           const int col = u.pn * 256 + bj * HALF + wc * 32 + 8 * fq;
;           const f32x4 v0 = acc[ai][bj][m][0], v1 = acc[ai][bj][m][1];
;           const int row = u.pm * 256 + rl;
;           u32x4 o; o.x = pk2(v0.x, v0.y); o.y = pk2(v0.z, v0.w); o.z = pk2(v1.x, v1.y); o.w = pk2(v1.z, v1.w);
;           *(u32x4*)(proj + (size_t)row * NPROJ + col) = o;
;           if (u.pn >= 8 && u.pn < 12) {
;             const int isv = u.pn >= 10; const int cc = col - (isv ? C_BV : C_BK);
;             float* dst = out + (isv ? O_VP : O_KP) + ((size_t)l * TP + row) * 512 + cc;
;             *(f32x4*)dst = v0; *(f32x4*)(dst + 4) = v1;
	ds_read_b128 v[160:163], v151 offset:49152
	ds_read_b128 v[164:167], v208 offset:49152
	ds_read_b128 v[168:171], v151 offset:51200
	ds_read_b128 v[172:175], v208 offset:51200
	ds_read_b128 v[176:179], v151 offset:53248
	ds_read_b128 v[180:183], v208 offset:53248
	ds_read_b128 v[184:187], v151 offset:55296
	ds_read_b128 v[188:191], v208 offset:55296
	global_load_lds_dwordx4 v[142:143], off
	v_lshl_add_u64 v[142:143], s[72:73], 0, v[130:131]
	s_mov_b32 m0, s65
	s_nop 0
	global_load_lds_dwordx4 v[142:143], off
	s_barrier
	s_waitcnt lgkmcnt(0)
	s_setprio 1
	s_waitcnt lgkmcnt(0)
	v_mfma_f32_16x16x32_bf16 v[60:63], v[134:137], v[160:163], v[60:63]
	v_mfma_f32_16x16x32_bf16 v[56:59], v[152:155], v[160:163], v[56:59]
	v_mfma_f32_16x16x32_bf16 v[44:47], v[134:137], v[168:171], v[44:47]
	v_mfma_f32_16x16x32_bf16 v[40:43], v[152:155], v[168:171], v[40:43]
	v_mfma_f32_16x16x32_bf16 v[28:31], v[134:137], v[176:179], v[28:31]
	v_mfma_f32_16x16x32_bf16 v[24:27], v[152:155], v[176:179], v[24:27]
	v_mfma_f32_16x16x32_bf16 v[12:15], v[134:137], v[184:187], v[12:15]
	v_mfma_f32_16x16x32_bf16 v[8:11], v[152:155], v[184:187], v[8:11]
	v_mfma_f32_16x16x32_bf16 v[60:63], v[138:141], v[164:167], v[60:63]
	v_mfma_f32_16x16x32_bf16 v[56:59], v[156:159], v[164:167], v[56:59]
	v_mfma_f32_16x16x32_bf16 v[44:47], v[138:141], v[172:175], v[44:47]
	v_mfma_f32_16x16x32_bf16 v[40:43], v[156:159], v[172:175], v[40:43]
	v_mfma_f32_16x16x32_bf16 v[28:31], v[138:141], v[180:183], v[28:31]
	v_mfma_f32_16x16x32_bf16 v[24:27], v[156:159], v[180:183], v[24:27]
	v_mfma_f32_16x16x32_bf16 v[12:15], v[138:141], v[188:191], v[12:15]
	v_mfma_f32_16x16x32_bf16 v[8:11], v[156:159], v[188:191], v[8:11]
	s_setprio 0
	s_barrier
	s_add_u32 s10, s70, 0x80000
	s_addc_u32 s11, s71, 0
	s_add_i32 s0, s1, s5
	v_lshl_add_u64 v[134:135], s[10:11], 0, v[146:147]
	s_mov_b32 m0, s0
	s_nop 0
	global_load_lds_dwordx4 v[134:135], off
	v_lshl_add_u64 v[134:135], s[10:11], 0, v[132:133]
	s_add_i32 m0, s0, 0x2000
	s_nop 0
	global_load_lds_dwordx4 v[134:135], off
	s_waitcnt vmcnt(6)
	s_barrier
	s_setprio 1
	v_mfma_f32_16x16x32_bf16 v[52:55], v[192:195], v[160:163], v[52:55]
	v_mfma_f32_16x16x32_bf16 v[48:51], v[200:203], v[160:163], v[48:51]
	v_mfma_f32_16x16x32_bf16 v[36:39], v[192:195], v[168:171], v[36:39]
	v_mfma_f32_16x16x32_bf16 v[32:35], v[200:203], v[168:171], v[32:35]
	v_mfma_f32_16x16x32_bf16 v[20:23], v[192:195], v[176:179], v[20:23]
	v_mfma_f32_16x16x32_bf16 v[16:19], v[200:203], v[176:179], v[16:19]
	v_mfma_f32_16x16x32_bf16 v[4:7], v[192:195], v[184:187], v[4:7]
	v_mfma_f32_16x16x32_bf16 v[0:3], v[200:203], v[184:187], v[0:3]
	v_mfma_f32_16x16x32_bf16 v[52:55], v[196:199], v[164:167], v[52:55]
	v_mfma_f32_16x16x32_bf16 v[48:51], v[204:207], v[164:167], v[48:51]
	v_mfma_f32_16x16x32_bf16 v[36:39], v[196:199], v[172:175], v[36:39]
	v_mfma_f32_16x16x32_bf16 v[32:35], v[204:207], v[172:175], v[32:35]
	v_mfma_f32_16x16x32_bf16 v[20:23], v[196:199], v[180:183], v[20:23]
	v_mfma_f32_16x16x32_bf16 v[16:19], v[204:207], v[180:183], v[16:19]
	v_mfma_f32_16x16x32_bf16 v[4:7], v[196:199], v[188:191], v[4:7]
	v_mfma_f32_16x16x32_bf16 v[0:3], v[204:207], v[188:191], v[0:3]
	s_setprio 0
	s_add_i32 s6, s6, 2
	s_addk_i32 s56, 0x100
	s_addk_i32 s7, 0x100
	s_cmp_gt_u32 s6, 29
	s_barrier
	s_cbranch_scc0 .LBB0_282
	v_mov_b32_e32 v135, v148
	v_mov_b32_e32 v134, v149
	s_lshl_b32 s0, s64, 8
	s_or_b32 s0, s0, s38
	v_lshl_add_u32 v134, v134, 3, s0
	s_lshl_b32 s0, s8, 8
	s_add_i32 s0, s0, s37
	v_add_u32_e32 v136, s0, v135
	s_and_b32 s0, s64, -4
	s_cmp_eq_u32 s0, 8
	s_cselect_b64 s[66:67], -1, 0
	s_cmp_gt_u32 s64, 9
	s_cselect_b64 s[6:7], -1, 0
	s_and_b64 s[6:7], s[6:7], exec
	s_movk_i32 s1, 0xf600
	v_mov_b64_e32 v[138:139], s[26:27]
	s_cselect_b32 s7, s1, 0xfffff800
	s_mov_b32 s1, 0x3040000
	v_ashrrev_i32_e32 v137, 31, v136
	v_mad_i64_i32 v[138:139], s[8:9], v136, s92, v[138:139]
	v_ashrrev_i32_e32 v135, 31, v134
	s_cselect_b32 s6, s1, 0x2040000
	s_cmp_lg_u32 s0, 8
	v_lshlrev_b64 v[140:141], 11, v[136:137]
	v_lshl_add_u64 v[142:143], v[134:135], 1, v[138:139]
	v_add_u32_e32 v138, s7, v134
	v_cvt_pk_bf16_f32 v152, v124, v125
	v_cvt_pk_bf16_f32 v153, v126, v127
	v_cvt_pk_bf16_f32 v154, v120, v121
	v_cvt_pk_bf16_f32 v155, v122, v123
	global_store_dwordx4 v[142:143], v[152:155], off
	s_cbranch_scc1 .LBB0_285
	s_lshl_b32 s0, s6, 2
	s_add_u32 s8, s83, s0
	s_addc_u32 s9, s86, 0
	v_lshl_add_u64 v[152:153], s[8:9], 0, v[140:141]
	v_ashrrev_i32_e32 v139, 31, v138
	v_lshl_add_u64 v[152:153], v[138:139], 2, v[152:153]
	global_store_dwordx4 v[152:153], v[124:127], off
	global_store_dwordx4 v[152:153], v[120:123], off offset:16
